# S5 chunk-final phase K loop as a 32-quad register ring (re-test on the current stack)
# speedup vs baseline: 1.0081x; 1.0006x over previous
; #define GAS __attribute__((address_space(1)))
; __device__ __forceinline__ void ph_s5_finals(Frame& F) {
;     ...
;     for (int u = F.vcu; u < 288; u += F.G) {
;         const int g = u / 9, nb = u % 9; int chunk = nb * 32 + r32; const bool valid = chunk < NCH; if (!valid) chunk = NCH - 1;
;         const bf16* ub = ug_frag_base(ws, g, nb, lane);
;         const bf16* wf = (const bf16*)(ws + WS_WF) + (size_t)g * 256 * 1024 + (((size_t)wave * 64) * 64 + lane) * 8;
;         f32x16 acc;
; #pragma unroll
;         for (int r = 0; r < 16; ++r) acc[r] = 0.f;
; #pragma unroll 16
;         for (int sI = 0; sI < 64; ++sI) { const bf16x8_t a = *(const GAS bf16x8_t*)(wf + 512 * sI), b = *(const GAS bf16x8_t*)(ub + 512 * sI); acc = __builtin_amdgcn_mfma_f32_32x32x16_bf16(a, b, acc, 0, 0, 0); }
.LBB0_593:
	s_mul_hi_i32 s0, s17, 0x38e38e39
	s_lshr_b32 s1, s0, 31
	s_ashr_i32 s0, s0, 1
	s_add_i32 s0, s0, s1
	s_mul_i32 s1, s0, 9
	s_sub_i32 s18, s17, s1
	s_cmp_lt_i32 s18, 8
	s_cselect_b64 s[2:3], -1, 0
	s_lshl_b32 s1, s0, 3
	s_add_i32 s1, s1, s18
	s_and_b64 s[2:3], s[2:3], exec
	s_cselect_b32 s2, s1, s0
	s_cselect_b32 s1, s6, 0xdc00000
	s_add_u32 s1, s4, s1
	s_addc_u32 s19, s5, 0
	s_ashr_i32 s3, s2, 31
	s_lshl_b64 s[2:3], s[2:3], 16
	s_add_u32 s2, s1, s2
	s_addc_u32 s3, s19, s3
	s_ashr_i32 s1, s0, 31
	s_lshl_b64 s[20:21], s[0:1], 19
	v_mov_b32_e32 v2, 0
	v_lshl_add_u64 v[26:27], s[2:3], 0, v[20:21]
	v_lshl_add_u64 v[28:29], v[24:25], 0, s[20:21]
	s_mov_b64 s[2:3], 0
	v_mov_b32_e32 v3, v2
	v_mov_b32_e32 v4, v2
	v_mov_b32_e32 v5, v2
	v_mov_b32_e32 v6, v2
	v_mov_b32_e32 v7, v2
	v_mov_b32_e32 v8, v2
	v_mov_b32_e32 v9, v2
	v_mov_b32_e32 v10, v2
	v_mov_b32_e32 v11, v2
	v_mov_b32_e32 v12, v2
	v_mov_b32_e32 v13, v2
	v_mov_b32_e32 v14, v2
	v_mov_b32_e32 v15, v2
	v_mov_b32_e32 v16, v2
	v_mov_b32_e32 v17, v2
	v_add_co_u32_e32 v218, vcc, 0x7ffc000, v28
	s_nop 1
	v_addc_co_u32_e32 v219, vcc, 0, v29, vcc
	v_add_co_u32_e32 v220, vcc, 0xffffc000, v26
	s_nop 1
	v_addc_co_u32_e32 v221, vcc, -1, v27, vcc
	v_add_co_u32_e32 v222, vcc, 0x5000, v218
	s_nop 1
	v_addc_co_u32_e32 v223, vcc, 0, v219, vcc
	v_add_co_u32_e32 v224, vcc, 0x7000, v218
	s_nop 1
	v_addc_co_u32_e32 v225, vcc, 0, v219, vcc
	v_add_co_u32_e32 v226, vcc, 0x5000, v220
	s_nop 1
	v_addc_co_u32_e32 v227, vcc, 0, v221, vcc
	v_add_co_u32_e32 v228, vcc, 0x7000, v220
	s_nop 1
	v_addc_co_u32_e32 v229, vcc, 0, v221, vcc
	global_load_dwordx4 v[90:93], v[222:223], off offset:-4096
	global_load_dwordx4 v[154:157], v[226:227], off offset:-4096
	global_load_dwordx4 v[94:97], v[222:223], off offset:-3072
	global_load_dwordx4 v[158:161], v[226:227], off offset:-3072
	global_load_dwordx4 v[98:101], v[222:223], off offset:-2048
	global_load_dwordx4 v[162:165], v[226:227], off offset:-2048
	global_load_dwordx4 v[102:105], v[222:223], off offset:-1024
	global_load_dwordx4 v[166:169], v[226:227], off offset:-1024
	global_load_dwordx4 v[106:109], v[222:223], off offset:0
	global_load_dwordx4 v[170:173], v[226:227], off offset:0
	global_load_dwordx4 v[110:113], v[222:223], off offset:1024
	global_load_dwordx4 v[174:177], v[226:227], off offset:1024
	global_load_dwordx4 v[114:117], v[222:223], off offset:2048
	global_load_dwordx4 v[178:181], v[226:227], off offset:2048
	global_load_dwordx4 v[118:121], v[222:223], off offset:3072
	global_load_dwordx4 v[182:185], v[226:227], off offset:3072
	global_load_dwordx4 v[122:125], v[224:225], off offset:-4096
	global_load_dwordx4 v[186:189], v[228:229], off offset:-4096
	global_load_dwordx4 v[126:129], v[224:225], off offset:-3072
	global_load_dwordx4 v[190:193], v[228:229], off offset:-3072
	global_load_dwordx4 v[130:133], v[224:225], off offset:-2048
	global_load_dwordx4 v[194:197], v[228:229], off offset:-2048
	global_load_dwordx4 v[134:137], v[224:225], off offset:-1024
	global_load_dwordx4 v[198:201], v[228:229], off offset:-1024
	global_load_dwordx4 v[138:141], v[224:225], off offset:0
	global_load_dwordx4 v[202:205], v[228:229], off offset:0
	global_load_dwordx4 v[142:145], v[224:225], off offset:1024
	global_load_dwordx4 v[206:209], v[228:229], off offset:1024
	global_load_dwordx4 v[146:149], v[224:225], off offset:2048
	global_load_dwordx4 v[210:213], v[228:229], off offset:2048
	global_load_dwordx4 v[150:153], v[224:225], off offset:3072
	global_load_dwordx4 v[214:217], v[228:229], off offset:3072
	v_add_co_u32_e32 v218, vcc, 0x4000, v218
	s_nop 1
	v_addc_co_u32_e32 v219, vcc, 0, v219, vcc
	v_add_co_u32_e32 v220, vcc, 0x4000, v220
	s_nop 1
	v_addc_co_u32_e32 v221, vcc, 0, v221, vcc
; #define GAS __attribute__((address_space(1)))
; __device__ __forceinline__ void ph_s5_finals(Frame& F) {
;     ...
; #pragma unroll 16
;         for (int sI = 0; sI < 64; ++sI) { const bf16x8_t a = *(const GAS bf16x8_t*)(wf + 512 * sI), b = *(const GAS bf16x8_t*)(ub + 512 * sI); acc = __builtin_amdgcn_mfma_f32_32x32x16_bf16(a, b, acc, 0, 0, 0); }
;         if (valid) { float* fo = (float*)(ws + WS_FIN) + ((size_t)g * NCH + chunk) * 256 + 32 * wave + 4 * hh;
; #pragma unroll
;             for (int k = 0; k < 4; ++k) *(GAS f32x4*)(fo + 8 * k) = (f32x4){acc[4 * k], acc[4 * k + 1], acc[4 * k + 2], acc[4 * k + 3]}; }
.LBB0_594:
	v_add_co_u32_e32 v222, vcc, 0x5000, v218
	s_nop 1
	v_addc_co_u32_e32 v223, vcc, 0, v219, vcc
	v_add_co_u32_e32 v224, vcc, 0x7000, v218
	s_nop 1
	v_addc_co_u32_e32 v225, vcc, 0, v219, vcc
	v_add_co_u32_e32 v226, vcc, 0x5000, v220
	s_nop 1
	v_addc_co_u32_e32 v227, vcc, 0, v221, vcc
	v_add_co_u32_e32 v228, vcc, 0x7000, v220
	s_nop 1
	v_addc_co_u32_e32 v229, vcc, 0, v221, vcc
	s_waitcnt vmcnt(30)
	v_mfma_f32_32x32x16_bf16 v[2:17], v[90:93], v[154:157], v[2:17]
	global_load_dwordx4 v[90:93], v[222:223], off offset:-4096
	global_load_dwordx4 v[154:157], v[226:227], off offset:-4096
	s_waitcnt vmcnt(30)
	v_mfma_f32_32x32x16_bf16 v[2:17], v[94:97], v[158:161], v[2:17]
	global_load_dwordx4 v[94:97], v[222:223], off offset:-3072
	global_load_dwordx4 v[158:161], v[226:227], off offset:-3072
	s_waitcnt vmcnt(30)
	v_mfma_f32_32x32x16_bf16 v[2:17], v[98:101], v[162:165], v[2:17]
	global_load_dwordx4 v[98:101], v[222:223], off offset:-2048
	global_load_dwordx4 v[162:165], v[226:227], off offset:-2048
	s_waitcnt vmcnt(30)
	v_mfma_f32_32x32x16_bf16 v[2:17], v[102:105], v[166:169], v[2:17]
	global_load_dwordx4 v[102:105], v[222:223], off offset:-1024
	global_load_dwordx4 v[166:169], v[226:227], off offset:-1024
	s_waitcnt vmcnt(30)
	v_mfma_f32_32x32x16_bf16 v[2:17], v[106:109], v[170:173], v[2:17]
	global_load_dwordx4 v[106:109], v[222:223], off offset:0
	global_load_dwordx4 v[170:173], v[226:227], off offset:0
	s_waitcnt vmcnt(30)
	v_mfma_f32_32x32x16_bf16 v[2:17], v[110:113], v[174:177], v[2:17]
	global_load_dwordx4 v[110:113], v[222:223], off offset:1024
	global_load_dwordx4 v[174:177], v[226:227], off offset:1024
	s_waitcnt vmcnt(30)
	v_mfma_f32_32x32x16_bf16 v[2:17], v[114:117], v[178:181], v[2:17]
	global_load_dwordx4 v[114:117], v[222:223], off offset:2048
	global_load_dwordx4 v[178:181], v[226:227], off offset:2048
	s_waitcnt vmcnt(30)
	v_mfma_f32_32x32x16_bf16 v[2:17], v[118:121], v[182:185], v[2:17]
	global_load_dwordx4 v[118:121], v[222:223], off offset:3072
	global_load_dwordx4 v[182:185], v[226:227], off offset:3072
	s_waitcnt vmcnt(30)
	v_mfma_f32_32x32x16_bf16 v[2:17], v[122:125], v[186:189], v[2:17]
	global_load_dwordx4 v[122:125], v[224:225], off offset:-4096
	global_load_dwordx4 v[186:189], v[228:229], off offset:-4096
	s_waitcnt vmcnt(30)
	v_mfma_f32_32x32x16_bf16 v[2:17], v[126:129], v[190:193], v[2:17]
	global_load_dwordx4 v[126:129], v[224:225], off offset:-3072
	global_load_dwordx4 v[190:193], v[228:229], off offset:-3072
	s_waitcnt vmcnt(30)
	v_mfma_f32_32x32x16_bf16 v[2:17], v[130:133], v[194:197], v[2:17]
	global_load_dwordx4 v[130:133], v[224:225], off offset:-2048
	global_load_dwordx4 v[194:197], v[228:229], off offset:-2048
	s_waitcnt vmcnt(30)
	v_mfma_f32_32x32x16_bf16 v[2:17], v[134:137], v[198:201], v[2:17]
	global_load_dwordx4 v[134:137], v[224:225], off offset:-1024
	global_load_dwordx4 v[198:201], v[228:229], off offset:-1024
	s_waitcnt vmcnt(30)
	v_mfma_f32_32x32x16_bf16 v[2:17], v[138:141], v[202:205], v[2:17]
	global_load_dwordx4 v[138:141], v[224:225], off offset:0
	global_load_dwordx4 v[202:205], v[228:229], off offset:0
	s_waitcnt vmcnt(30)
	v_mfma_f32_32x32x16_bf16 v[2:17], v[142:145], v[206:209], v[2:17]
	global_load_dwordx4 v[142:145], v[224:225], off offset:1024
	global_load_dwordx4 v[206:209], v[228:229], off offset:1024
	s_waitcnt vmcnt(30)
	v_mfma_f32_32x32x16_bf16 v[2:17], v[146:149], v[210:213], v[2:17]
	global_load_dwordx4 v[146:149], v[224:225], off offset:2048
	global_load_dwordx4 v[210:213], v[228:229], off offset:2048
	s_waitcnt vmcnt(30)
	v_mfma_f32_32x32x16_bf16 v[2:17], v[150:153], v[214:217], v[2:17]
	global_load_dwordx4 v[150:153], v[224:225], off offset:3072
	global_load_dwordx4 v[214:217], v[228:229], off offset:3072
	v_add_co_u32_e32 v218, vcc, 0x4000, v218
	s_nop 1
	v_addc_co_u32_e32 v219, vcc, 0, v219, vcc
	v_add_co_u32_e32 v220, vcc, 0x4000, v220
	s_nop 1
	v_addc_co_u32_e32 v221, vcc, 0, v221, vcc
	s_add_u32 s2, s2, 0x4000
	s_addc_u32 s3, s3, 0
	s_cmp_eq_u32 s2, 0x10000
	s_cbranch_scc0 .LBB0_594
	v_lshl_or_b32 v26, s18, 5, v1
	v_cmp_gt_i32_e32 vcc, s16, v26
	s_and_saveexec_b64 s[2:3], vcc
	s_cbranch_execz .LBB0_592
	v_ashrrev_i32_e32 v27, 31, v26
	v_mad_i64_i32 v[26:27], s[0:1], s0, v30, v[26:27]
	v_lshlrev_b64 v[26:27], 10, v[26:27]
	v_lshl_add_u64 v[26:27], v[22:23], 0, v[26:27]
	s_nop 2
	global_store_dwordx4 v[26:27], v[2:5], off
	global_store_dwordx4 v[26:27], v[6:9], off offset:32
	global_store_dwordx4 v[26:27], v[10:13], off offset:64
	global_store_dwordx4 v[26:27], v[14:17], off offset:96
	s_branch .LBB0_592
